# MLA S2: post-exp sum check replaces pre-exp max tree (exps into separate bank, exact max path kept as fallback); XCD-aware unit map; rendezvous after 15th MFMA
# speedup vs baseline: 1.0817x; 1.0249x over previous
; __device__ __forceinline__ int opaque_tid() { int t = threadIdx.x; asm volatile("" : "+v"(t)); return t; }
; #define PHASE_ARGS() PHASE_LOADP(); unsigned char* ws = P.ws; \
;     const float* modbuf = (const float*)(ws + WS_MOD); const float2* rope = (const float2*)(ws + WS_ROPE); (void)modbuf; (void)rope
; __device__ __forceinline__ void mla_unit2(const Params& P, unsigned char* lds, int h, int rb, int grp, bool dry = false) {
;     const int tid = opaque_tid(), lane = tid & 63, r32 = lane & 31, hi = lane >> 5; const int wid = __builtin_amdgcn_readfirstlane(tid >> 6);
;     const int hoff = wid >> 2;
;     unsigned char* ws = P.ws;
;     const int l = grp ? 16384 : 2048; const size_t rowoff = grp ? M_A : 0; const int m0 = rb * 256; const int seq0 = m0 & ~(l - 1), t0 = m0 - seq0;
;     const bf16_t* Qp = (const bf16_t*)(ws + WS_QG) + h * 96; const bf16_t* Kp = (const bf16_t*)(ws + WS_KG) + h * 64; const bf16_t* Vp = (const bf16_t*)(ws + WS_VG) + h * 64;
;     const bf16_t* Kpe = (const bf16_t*)(ws + WS_KPE) + rowoff * 32; bf16_t* Gp = (bf16_t*)(ws + WS_U1) + rowoff * OD_INP + 416 + h * 64; const int ldg = OD_INP;
;     const int NT = l >> 6;
;     bf16x8 qr[6];
;     { const bf16_t* Qw = Qp + (size_t)(seq0 + t0 + wid * 32 + r32) * 1536 + hi * 8;
; #pragma unroll
;       for (int d0 = 0; d0 < 6; ++d0) qr[d0] = *(const bf16x8*)(Qw + d0 * 16); }
; __global__ void __launch_bounds__(512, 2) mega_fwd(Params Pk) {
;     ...
;         for (int u = bx; u < 2048; u += G) { PHASE_ARGS(); mla_unit2(P, lds, u >> 7, u & 127, grp); }
.LBB0_925:
	s_mov_b64 s[4:5], s[0:1]
	s_load_dwordx2 s[36:37], s[4:5], 0xa0
	s_and_b32 s66, s56, 7
	s_lshl_b32 s66, s66, 5
	s_bfe_u32 s67, s56, 0x50003
	s_or_b32 s66, s66, s67
	s_andn2_b32 s67, s56, 0xff
	s_or_b32 s67, s67, s66
	s_ashr_i32 s8, s67, 7
	s_mul_i32 s4, s8, 0x60
	s_lshl_b32 s9, s67, 8
	s_ashr_i32 s5, s4, 31
	s_and_b32 s10, s9, 0x7f00
	s_lshl_b64 s[4:5], s[4:5], 1
	s_waitcnt lgkmcnt(0)
	s_add_u32 s4, s36, s4
	v_mov_b32_e32 v160, v254
	s_addc_u32 s5, s37, s5
	s_add_u32 s4, s4, 0xe000000
	v_readfirstlane_b32 s58, v160
	s_addc_u32 s5, s5, 0
	s_lshl_b32 s42, s8, 6
	s_ashr_i32 s8, s58, 1
	s_and_b32 s57, s8, 0xffffffe0
	v_and_b32_e32 v195, 31, v160
	s_add_i32 s57, s57, s10
	v_bfe_u32 v194, v160, 5, 1
	v_or_b32_e32 v2, s57, v195
	v_mov_b64_e32 v[0:1], s[4:5]
	s_ashr_i32 s43, s42, 31
	v_mad_i64_i32 v[0:1], s[4:5], v2, s89, v[0:1]
	v_lshlrev_b32_e32 v154, 4, v194
	v_mov_b32_e32 v155, v145
	s_and_b32 s10, s9, s20
	v_ashrrev_i32_e32 v11, 3, v160
	v_lshl_add_u64 v[0:1], v[0:1], 0, v[154:155]
	s_ashr_i32 s40, s58, 8
	s_lshl_b64 s[38:39], s[42:43], 1
	v_add_u32_e32 v8, s10, v11
	global_load_dwordx4 v[96:99], v[0:1], off
	global_load_dwordx4 v[100:103], v[0:1], off offset:32
	global_load_dwordx4 v[104:107], v[0:1], off offset:64
	global_load_dwordx4 v[108:111], v[0:1], off offset:96
	global_load_dwordx4 v[112:115], v[0:1], off offset:128
	global_load_dwordx4 v[116:119], v[0:1], off offset:160
	s_add_u32 s4, s36, s38
	v_lshlrev_b32_e32 v0, 3, v160
	v_ashrrev_i32_e32 v9, 31, v8
	s_addc_u32 s5, s37, s39
	v_and_b32_e32 v12, 56, v0
	v_lshlrev_b64 v[94:95], 11, v[8:9]
	v_bfe_u32 v10, v160, 2, 6
	v_and_b32_e32 v2, 24, v0
	v_lshl_add_u64 v[0:1], s[4:5], 0, v[94:95]
	v_lshlrev_b32_e32 v144, 1, v12
	s_add_u32 s8, s36, s52
	v_lshl_add_u64 v[14:15], v[0:1], 0, v[144:145]
	v_or_b32_e32 v0, s10, v10
	s_addc_u32 s9, s37, 0
	v_lshlrev_b32_e32 v92, 6, v0
	v_mov_b32_e32 v93, v145
	v_lshl_add_u64 v[0:1], s[8:9], 0, v[92:93]
	v_lshlrev_b32_e32 v156, 1, v2
	v_mov_b32_e32 v157, v145
	v_lshl_add_u64 v[16:17], v[0:1], 0, v[156:157]
	v_add_co_u32_e32 v0, vcc, s90, v14
	s_mov_b64 s[4:5], 0x14000000
	s_nop 0
	v_addc_co_u32_e32 v1, vcc, 0, v15, vcc
	v_add_co_u32_e32 v2, vcc, 0x300000, v16
	s_add_i32 s48, s40, 1
	s_nop 0
	v_addc_co_u32_e32 v3, vcc, 0, v17, vcc
	global_load_dwordx4 v[4:7], v[0:1], off
	s_nop 0
	global_load_dwordx4 v[0:3], v[2:3], off
	v_lshl_add_u64 v[32:33], v[14:15], 0, s[4:5]
	s_cmp_lt_i32 s48, s54
	s_mov_b64 s[4:5], 0x300000
	s_cselect_b64 s[50:51], -1, 0
	s_cmp_ge_i32 s48, s54
	v_lshl_add_u64 v[34:35], v[16:17], 0, s[4:5]
	s_cbranch_scc1 .LBB0_927
	s_ashr_i32 s49, s48, 31
	s_lshl_b64 s[4:5], s[48:49], 17
	v_lshl_add_u64 v[14:15], v[32:33], 0, s[4:5]
	s_lshl_b64 s[4:5], s[48:49], 12
	v_lshl_add_u64 v[16:17], v[34:35], 0, s[4:5]
	global_load_dwordx4 v[120:123], v[14:15], off
	global_load_dwordx4 v[124:127], v[16:17], off

.LBB0_963:
	s_or_b64 exec, exec, s[12:13]
	s_waitcnt lgkmcnt(0)
	v_add_u32_e32 v210, s46, v154
	ds_read_b128 v[182:185], v210 offset:43232
	ds_read_b128 v[186:189], v210 offset:43200
	ds_read_b128 v[190:193], v210 offset:43168
	ds_read_b128 v[206:209], v210 offset:43136
	s_waitcnt lgkmcnt(0)
	s_waitcnt lgkmcnt(3)
	v_pk_mul_f32 v[12:13], v[12:13], v[182:183]
	s_waitcnt lgkmcnt(2)
	v_pk_mul_f32 v[8:9], v[8:9], v[186:187]
	s_waitcnt lgkmcnt(1)
	v_pk_mul_f32 v[4:5], v[4:5], v[190:191]
	v_pk_mul_f32 v[14:15], v[14:15], v[184:185]
	v_pk_mul_f32 v[10:11], v[10:11], v[188:189]
	v_pk_mul_f32 v[6:7], v[6:7], v[192:193]
	s_waitcnt lgkmcnt(0)
	v_pk_mul_f32 v[2:3], v[2:3], v[208:209]
	v_pk_mul_f32 v[0:1], v[0:1], v[206:207]
	v_pk_mul_f32 v[28:29], v[28:29], v[182:183]
	v_pk_mul_f32 v[24:25], v[24:25], v[186:187]
	v_pk_mul_f32 v[20:21], v[20:21], v[190:191]
	v_pk_mul_f32 v[30:31], v[30:31], v[184:185]
	v_pk_mul_f32 v[26:27], v[26:27], v[188:189]
	v_pk_mul_f32 v[22:23], v[22:23], v[192:193]
	v_pk_mul_f32 v[18:19], v[18:19], v[208:209]
	v_pk_mul_f32 v[16:17], v[16:17], v[206:207]
	v_mov_b32_e32 v235, 1.0

; __device__ __forceinline__ unsigned cvt_pk_bf16(float lo, float hi) { unsigned r; asm volatile("v_cvt_pk_bf16_f32 %0, %1, %2" : "=v"(r) : "v"(lo), "v"(hi)); return r; }
; __device__ __forceinline__ bf16x8 pack8(const f32x16& p, int base) {
;     u32x4 w = {cvt_pk_bf16(p[base + 0], p[base + 1]), cvt_pk_bf16(p[base + 2], p[base + 3]), cvt_pk_bf16(p[base + 4], p[base + 5]), cvt_pk_bf16(p[base + 6], p[base + 7])};
;     return *reinterpret_cast<bf16x8*>(&w);
; }
.Lmla_nobar7:
	s_add_u32 s60, s60, 0x20000
	s_addc_u32 s61, s61, 0
	s_add_u32 s62, s62, 0x20000
	s_addc_u32 s63, s63, 0
	s_add_u32 s64, s64, 0x1000
	s_addc_u32 s65, s65, 0
	s_cmp_lt_u32 s41, s54
	s_cbranch_scc0 .Lmla_exit_pack
	ds_read_b128 v[80:83], v157
	ds_read_b128 v[146:149], v157 offset:32
	ds_read_b128 v[150:153], v157 offset:6656
	ds_read_b128 v[168:171], v157 offset:6688
	v_cvt_pk_bf16_f32 v55, v245, v246
	v_cvt_pk_bf16_f32 v54, v243, v244
	v_cvt_pk_bf16_f32 v52, v234, v240
	v_cvt_pk_bf16_f32 v53, v241, v242
	v_cvt_pk_bf16_f32 v48, v247, v248
	v_cvt_pk_bf16_f32 v49, v249, v250
	v_cvt_pk_bf16_f32 v50, v251, v252
	v_cvt_pk_bf16_f32 v51, v253, v172
	v_cvt_pk_bf16_f32 v60, v218, v219
	v_cvt_pk_bf16_f32 v61, v220, v221
	v_cvt_pk_bf16_f32 v62, v222, v223
	v_cvt_pk_bf16_f32 v63, v224, v225
	v_cvt_pk_bf16_f32 v56, v226, v227
	v_cvt_pk_bf16_f32 v57, v228, v229
	v_cvt_pk_bf16_f32 v58, v230, v231
	v_cvt_pk_bf16_f32 v59, v232, v233
	s_branch .Lmla_s1e_body

; __device__ __forceinline__ void mla_softmax_rel_kp(f32x16& p0, f32x16& p1, f32x16& negm, bool first, float& l_reg, float& alpha, bf16x8& pa0, bf16x8& pa1, bf16x8& pa2, bf16x8& pa3) {
;     float pmax = p0[0];
; #pragma unroll
;     for (int r = 1; r < 16; ++r) pmax = fmaxf(pmax, p0[r]);
; #pragma unroll
;     for (int r = 0; r < 16; ++r) pmax = fmaxf(pmax, p1[r]);
;     { auto rr = __builtin_amdgcn_permlane32_swap(__float_as_uint(pmax), __float_as_uint(pmax), false, false); pmax = fmaxf(__uint_as_float(rr[0]), __uint_as_float(rr[1])); }
;     alpha = 1.f;
;     if (__builtin_expect(first || !__all(pmax <= THR2), 0)) {
;         const float d = first ? pmax : fmaxf(pmax, 0.f);
;         if (!first) alpha = __builtin_amdgcn_exp2f(-d);
;         const float nm = negm[0] - d;
; #pragma unroll
;         for (int r = 0; r < 16; ++r) { negm[r] = nm; p0[r] -= d; p1[r] -= d; }
;     }
; #pragma unroll
;     for (int r = 0; r < 16; ++r) { p0[r] = __builtin_amdgcn_exp2f(p0[r]); p1[r] = __builtin_amdgcn_exp2f(p1[r]); }
;     float ps = 0.f;
; #pragma unroll
;     for (int r = 0; r < 16; ++r) ps += p0[r];
; #pragma unroll
;     for (int r = 0; r < 16; ++r) ps += p1[r];
;     { auto rr = __builtin_amdgcn_permlane32_swap(__float_as_uint(ps), __float_as_uint(ps), false, false); ps = __uint_as_float(rr[0]) + __uint_as_float(rr[1]); }
;     l_reg = l_reg * alpha + ps;
; __device__ __forceinline__ void pv_both_kp(f32x16& o0, f32x16& o1, int vb, bf16x8 pa0, bf16x8 pa1, bf16x8 pa2, bf16x8 pa3) {
;     const s16x4 l0 = tr_read<v_rd_off_kp(0, 0, 0)>(vb), h0 = tr_read<v_rd_off_kp(0, 0, 1)>(vb), l1 = tr_read<v_rd_off_kp(0, 1, 0)>(vb), h1 = tr_read<v_rd_off_kp(0, 1, 1)>(vb);
;     const s16x4 l2 = tr_read<v_rd_off_kp(0, 2, 0)>(vb), h2 = tr_read<v_rd_off_kp(0, 2, 1)>(vb), l3 = tr_read<v_rd_off_kp(0, 3, 0)>(vb), h3 = tr_read<v_rd_off_kp(0, 3, 1)>(vb);
;     const s16x4 m0 = tr_read<v_rd_off_kp(1, 0, 0)>(vb), n0 = tr_read<v_rd_off_kp(1, 0, 1)>(vb), m1 = tr_read<v_rd_off_kp(1, 1, 0)>(vb), n1 = tr_read<v_rd_off_kp(1, 1, 1)>(vb);
;     const s16x4 m2 = tr_read<v_rd_off_kp(1, 2, 0)>(vb), n2 = tr_read<v_rd_off_kp(1, 2, 1)>(vb), m3 = tr_read<v_rd_off_kp(1, 3, 0)>(vb), n3 = tr_read<v_rd_off_kp(1, 3, 1)>(vb);
;     asm volatile("s_waitcnt lgkmcnt(8)" ::: "memory"); __builtin_amdgcn_sched_barrier(0);
;     ...
;     o0 = __builtin_amdgcn_mfma_f32_32x32x16_bf16(pa0, PK(l0, h0), o0, 0, 0, 0);
.LBB0_969:
	s_waitcnt lgkmcnt(3)
	v_mfma_f32_32x32x16_bf16 v[64:79], v[80:83], v[96:99], v[32:47]
	s_waitcnt lgkmcnt(1)
	v_mfma_f32_32x32x16_bf16 v[80:95], v[150:153], v[96:99], v[32:47]
	v_mfma_f32_32x32x16_bf16 v[64:79], v[146:149], v[100:103], v[64:79]
	ds_read_b128 v[146:149], v157 offset:64
	ds_read_b128 v[150:153], v157 offset:96
	s_waitcnt lgkmcnt(2)
	v_mfma_f32_32x32x16_bf16 v[80:95], v[168:171], v[100:103], v[80:95]
	s_waitcnt lgkmcnt(1)
	v_mfma_f32_32x32x16_bf16 v[64:79], v[146:149], v[104:107], v[64:79]
	ds_read_b128 v[146:149], v157 offset:6720
	ds_read_b128 v[168:171], v157 offset:6752
	s_waitcnt lgkmcnt(1)
	v_mfma_f32_32x32x16_bf16 v[80:95], v[146:149], v[104:107], v[80:95]
	v_mfma_f32_32x32x16_bf16 v[64:79], v[150:153], v[108:111], v[64:79]
	ds_read_b128 v[146:149], v157 offset:128
	ds_read_b128 v[150:153], v157 offset:160
	s_waitcnt lgkmcnt(2)
	v_mfma_f32_32x32x16_bf16 v[80:95], v[168:171], v[108:111], v[80:95]
	s_waitcnt lgkmcnt(1)
	v_mfma_f32_32x32x16_bf16 v[64:79], v[146:149], v[112:115], v[64:79]
	ds_read_b128 v[146:149], v157 offset:6784
	ds_read_b128 v[168:171], v157 offset:6816
	ds_read_b64_tr_b16 v[182:183], v204 offset:0
	ds_read_b64_tr_b16 v[184:185], v204 offset:0x100
	s_waitcnt lgkmcnt(1)
	v_mfma_f32_32x32x16_bf16 v[80:95], v[146:149], v[112:115], v[80:95]
	ds_read_b64_tr_b16 v[146:147], v204 offset:0x800
	ds_read_b64_tr_b16 v[148:149], v204 offset:0x900
	ds_read_b64_tr_b16 v[186:187], v204 offset:0x1000
	ds_read_b64_tr_b16 v[188:189], v204 offset:0x1100
	ds_read_b64_tr_b16 v[190:191], v204 offset:0x1800
	ds_read_b64_tr_b16 v[192:193], v204 offset:0x1900
	ds_read_b64_tr_b16 v[206:207], v204 offset:0x200
	ds_read_b64_tr_b16 v[208:209], v204 offset:0x300
	v_mfma_f32_32x32x16_bf16 v[64:79], v[150:153], v[116:119], v[64:79]
	ds_read_b64_tr_b16 v[150:151], v204 offset:0xa00
	ds_read_b64_tr_b16 v[152:153], v204 offset:0xb00
	ds_read_b64_tr_b16 v[210:211], v204 offset:0x1200
	ds_read_b64_tr_b16 v[212:213], v204 offset:0x1300
	ds_read_b64_tr_b16 v[214:215], v204 offset:0x1a00
	ds_read_b64_tr_b16 v[216:217], v204 offset:0x1b00
	s_waitcnt lgkmcnt(8)
	s_waitcnt lgkmcnt(0)
	v_mfma_f32_32x32x16_bf16 v[80:95], v[168:171], v[116:119], v[80:95]
	v_mfma_f32_32x32x16_bf16 v[0:15], v[60:63], v[182:185], v[0:15]
	s_waitcnt lgkmcnt(0)
	v_mfma_f32_32x32x16_bf16 v[0:15], v[56:59], v[146:149], v[0:15]
	v_mfma_f32_32x32x16_bf16 v[0:15], v[52:55], v[186:189], v[0:15]
	s_waitcnt lgkmcnt(0)
	s_cmp_lg_u32 s40, 0
	s_cbranch_scc0 .Lmla_nobar4
	s_barrier
.Lmla_nobar4:
	v_mfma_f32_32x32x16_bf16 v[0:15], v[48:51], v[190:193], v[0:15]
	v_mfma_f32_32x32x16_bf16 v[16:31], v[60:63], v[206:209], v[16:31]
	s_waitcnt lgkmcnt(0)
	v_mfma_f32_32x32x16_bf16 v[16:31], v[56:59], v[150:153], v[16:31]
	v_mfma_f32_32x32x16_bf16 v[16:31], v[52:55], v[210:213], v[16:31]
	v_mfma_f32_32x32x16_bf16 v[16:31], v[48:51], v[214:217], v[16:31]
	s_cmp_lg_u64 s[44:45], 0
	s_cbranch_scc0 .Lmla_w1_tail
	s_waitcnt vmcnt(3)
	ds_write_b128 v196, v[120:123]
	ds_write_b128 v197, v[128:131] offset:26624
	s_cmp_lg_u32 s8, 0
	s_cbranch_scc0 .LBB0_975
	ds_write_b128 v238, v[124:127] offset:128
.LBB0_975:
	v_exp_f32_e32 v218, v64
	v_exp_f32_e32 v219, v65
	v_exp_f32_e32 v220, v66
	v_exp_f32_e32 v221, v67
	v_add_f32_e32 v173, v218, v220
	v_exp_f32_e32 v222, v68
	v_add_f32_e32 v174, v219, v221
	v_exp_f32_e32 v223, v69
	v_add_f32_e32 v173, v222, v173
	v_exp_f32_e32 v224, v70
	v_add_f32_e32 v174, v223, v174
	v_exp_f32_e32 v225, v71
	v_add_f32_e32 v173, v224, v173
	v_exp_f32_e32 v226, v72
	v_add_f32_e32 v174, v225, v174
	v_exp_f32_e32 v227, v73
	v_add_f32_e32 v173, v226, v173
	v_exp_f32_e32 v228, v74
	v_add_f32_e32 v174, v227, v174
	v_exp_f32_e32 v229, v75
	v_add_f32_e32 v173, v228, v173
	v_exp_f32_e32 v230, v76
	v_add_f32_e32 v174, v229, v174
	v_exp_f32_e32 v231, v77
	v_add_f32_e32 v173, v230, v173
	v_exp_f32_e32 v232, v78
	v_add_f32_e32 v174, v231, v174
	v_exp_f32_e32 v233, v79
	v_add_f32_e32 v173, v232, v173
	v_exp_f32_e32 v234, v80
	v_add_f32_e32 v174, v233, v174
	v_exp_f32_e32 v240, v81
	v_add_f32_e32 v173, v234, v173
	v_exp_f32_e32 v241, v82
	v_add_f32_e32 v174, v240, v174
	v_exp_f32_e32 v242, v83
	v_add_f32_e32 v173, v241, v173
	v_exp_f32_e32 v243, v84
	v_add_f32_e32 v174, v242, v174
	v_exp_f32_e32 v244, v85
	v_add_f32_e32 v173, v243, v173
	v_exp_f32_e32 v245, v86
	v_add_f32_e32 v174, v244, v174
	v_exp_f32_e32 v246, v87
	v_add_f32_e32 v173, v245, v173
	v_exp_f32_e32 v247, v88
	v_add_f32_e32 v174, v246, v174
	v_exp_f32_e32 v248, v89
	v_add_f32_e32 v173, v247, v173
	v_exp_f32_e32 v249, v90
	v_add_f32_e32 v174, v248, v174
	v_exp_f32_e32 v250, v91
	v_add_f32_e32 v173, v249, v173
	v_exp_f32_e32 v251, v92
	v_add_f32_e32 v174, v250, v174
	v_exp_f32_e32 v252, v93
	v_add_f32_e32 v173, v251, v173
	v_exp_f32_e32 v253, v94
	v_add_f32_e32 v174, v252, v174
	v_exp_f32_e32 v172, v95
	v_add_f32_e32 v173, v253, v173
	v_add_f32_e32 v174, v172, v174
	v_add_f32_e32 v173, v173, v174
	v_cmp_ge_f32_e32 vcc, 0x47800000, v173
	s_cmp_eq_u64 vcc, exec
	s_cbranch_scc0 .LBB0_995
	v_add_f32_e32 v236, v236, v173
.Lmla_s2e_done:
	v_cmp_gt_f32_e32 vcc, 1.0, v144
	s_cbranch_vccz .LBB0_981
	s_and_saveexec_b64 s[12:13], s[10:11]
	ds_write_b32 v202, v144 offset:43136
	s_or_b64 exec, exec, s[12:13]
	s_waitcnt lgkmcnt(0)
	v_add_u32_e32 v210, s46, v154
	ds_read_b128 v[182:185], v210 offset:43232
	ds_read_b128 v[186:189], v210 offset:43200
	ds_read_b128 v[190:193], v210 offset:43168
	ds_read_b128 v[206:209], v210 offset:43136
	s_waitcnt lgkmcnt(0)
	s_waitcnt lgkmcnt(3)
	v_pk_mul_f32 v[12:13], v[12:13], v[182:183]
	s_waitcnt lgkmcnt(2)
	v_pk_mul_f32 v[8:9], v[8:9], v[186:187]
	s_waitcnt lgkmcnt(1)
	v_pk_mul_f32 v[4:5], v[4:5], v[190:191]
	v_pk_mul_f32 v[14:15], v[14:15], v[184:185]
	v_pk_mul_f32 v[10:11], v[10:11], v[188:189]
	v_pk_mul_f32 v[6:7], v[6:7], v[192:193]
	s_waitcnt lgkmcnt(0)
	v_pk_mul_f32 v[2:3], v[2:3], v[208:209]
	v_pk_mul_f32 v[0:1], v[0:1], v[206:207]
	v_pk_mul_f32 v[28:29], v[28:29], v[182:183]
	v_pk_mul_f32 v[24:25], v[24:25], v[186:187]
	v_pk_mul_f32 v[20:21], v[20:21], v[190:191]
	v_pk_mul_f32 v[30:31], v[30:31], v[184:185]
	v_pk_mul_f32 v[26:27], v[26:27], v[188:189]
	v_pk_mul_f32 v[22:23], v[22:23], v[192:193]
	v_pk_mul_f32 v[18:19], v[18:19], v[208:209]
	v_pk_mul_f32 v[16:17], v[16:17], v[206:207]
	v_mov_b32_e32 v144, 1.0

; __device__ __forceinline__ unsigned cvt_pk_bf16(float lo, float hi) { unsigned r; asm volatile("v_cvt_pk_bf16_f32 %0, %1, %2" : "=v"(r) : "v"(lo), "v"(hi)); return r; }
; __device__ __forceinline__ bf16x8 pack8(const f32x16& p, int base) {
;     u32x4 w = {cvt_pk_bf16(p[base + 0], p[base + 1]), cvt_pk_bf16(p[base + 2], p[base + 3]), cvt_pk_bf16(p[base + 4], p[base + 5]), cvt_pk_bf16(p[base + 6], p[base + 7])};
;     return *reinterpret_cast<bf16x8*>(&w);
; }
.Lmla_nobar5:
	ds_read_b128 v[146:149], v157 offset:13312
	ds_read_b128 v[150:153], v157 offset:13344
	v_cvt_pk_bf16_f32 v87, v245, v246
	v_cvt_pk_bf16_f32 v86, v243, v244
	v_cvt_pk_bf16_f32 v85, v241, v242
	v_cvt_pk_bf16_f32 v84, v234, v240
	v_cvt_pk_bf16_f32 v82, v251, v252
	v_cvt_pk_bf16_f32 v83, v253, v172
	v_cvt_pk_bf16_f32 v80, v247, v248
	v_cvt_pk_bf16_f32 v81, v249, v250
	v_cvt_pk_bf16_f32 v92, v218, v219
	v_cvt_pk_bf16_f32 v93, v220, v221
	v_cvt_pk_bf16_f32 v94, v222, v223
	v_cvt_pk_bf16_f32 v95, v224, v225
	v_cvt_pk_bf16_f32 v88, v226, v227
	v_cvt_pk_bf16_f32 v89, v228, v229
	v_cvt_pk_bf16_f32 v90, v230, v231
	v_cvt_pk_bf16_f32 v91, v232, v233
	s_add_u32 s60, s60, 0x20000
	s_addc_u32 s61, s61, 0
	s_add_u32 s62, s62, 0x20000
	s_addc_u32 s63, s63, 0
	s_add_u32 s64, s64, 0x1000
	s_addc_u32 s65, s65, 0
	s_add_i32 s47, s47, 3
	s_cmp_ge_i32 s47, s54
	s_cbranch_scc1 .LBB0_983
	global_load_dwordx4 v[120:123], v166, s[60:61]
	global_load_dwordx4 v[124:127], v167, s[64:65]

; __device__ __forceinline__ void mla_softmax_rel_kp(f32x16& p0, f32x16& p1, f32x16& negm, bool first, float& l_reg, float& alpha, bf16x8& pa0, bf16x8& pa1, bf16x8& pa2, bf16x8& pa3) {
;     float pmax = p0[0];
; #pragma unroll
;     for (int r = 1; r < 16; ++r) pmax = fmaxf(pmax, p0[r]);
; #pragma unroll
;     for (int r = 0; r < 16; ++r) pmax = fmaxf(pmax, p1[r]);
;     { auto rr = __builtin_amdgcn_permlane32_swap(__float_as_uint(pmax), __float_as_uint(pmax), false, false); pmax = fmaxf(__uint_as_float(rr[0]), __uint_as_float(rr[1])); }
;     alpha = 1.f;
;     if (__builtin_expect(first || !__all(pmax <= THR2), 0)) {
;         const float d = first ? pmax : fmaxf(pmax, 0.f);
;         if (!first) alpha = __builtin_amdgcn_exp2f(-d);
;         const float nm = negm[0] - d;
; #pragma unroll
;         for (int r = 0; r < 16; ++r) { negm[r] = nm; p0[r] -= d; p1[r] -= d; }
;     }
; #pragma unroll
;     for (int r = 0; r < 16; ++r) { p0[r] = __builtin_amdgcn_exp2f(p0[r]); p1[r] = __builtin_amdgcn_exp2f(p1[r]); }
;     float ps = 0.f;
; #pragma unroll
;     for (int r = 0; r < 16; ++r) ps += p0[r];
; #pragma unroll
;     for (int r = 0; r < 16; ++r) ps += p1[r];
;     { auto rr = __builtin_amdgcn_permlane32_swap(__float_as_uint(ps), __float_as_uint(ps), false, false); ps = __uint_as_float(rr[0]) + __uint_as_float(rr[1]); }
;     l_reg = l_reg * alpha + ps;
; __device__ __forceinline__ void pv_both_kp(f32x16& o0, f32x16& o1, int vb, bf16x8 pa0, bf16x8 pa1, bf16x8 pa2, bf16x8 pa3) {
;     const s16x4 l0 = tr_read<v_rd_off_kp(0, 0, 0)>(vb), h0 = tr_read<v_rd_off_kp(0, 0, 1)>(vb), l1 = tr_read<v_rd_off_kp(0, 1, 0)>(vb), h1 = tr_read<v_rd_off_kp(0, 1, 1)>(vb);
;     const s16x4 l2 = tr_read<v_rd_off_kp(0, 2, 0)>(vb), h2 = tr_read<v_rd_off_kp(0, 2, 1)>(vb), l3 = tr_read<v_rd_off_kp(0, 3, 0)>(vb), h3 = tr_read<v_rd_off_kp(0, 3, 1)>(vb);
;     const s16x4 m0 = tr_read<v_rd_off_kp(1, 0, 0)>(vb), n0 = tr_read<v_rd_off_kp(1, 0, 1)>(vb), m1 = tr_read<v_rd_off_kp(1, 1, 0)>(vb), n1 = tr_read<v_rd_off_kp(1, 1, 1)>(vb);
;     const s16x4 m2 = tr_read<v_rd_off_kp(1, 2, 0)>(vb), n2 = tr_read<v_rd_off_kp(1, 2, 1)>(vb), m3 = tr_read<v_rd_off_kp(1, 3, 0)>(vb), n3 = tr_read<v_rd_off_kp(1, 3, 1)>(vb);
;     asm volatile("s_waitcnt lgkmcnt(8)" ::: "memory"); __builtin_amdgcn_sched_barrier(0);
;     ...
;     o0 = __builtin_amdgcn_mfma_f32_32x32x16_bf16(pa0, PK(l0, h0), o0, 0, 0, 0);
.LBB0_985:
	s_waitcnt lgkmcnt(1)
	v_mfma_f32_32x32x16_bf16 v[64:79], v[146:149], v[96:99], v[32:47]
	ds_read_b128 v[146:149], v157 offset:19968
	ds_read_b128 v[162:165], v157 offset:20000
	s_waitcnt lgkmcnt(1)
	v_mfma_f32_32x32x16_bf16 v[48:63], v[146:149], v[96:99], v[32:47]
	v_mfma_f32_32x32x16_bf16 v[64:79], v[150:153], v[100:103], v[64:79]
	ds_read_b128 v[146:149], v157 offset:13376
	ds_read_b128 v[150:153], v157 offset:13408
	s_waitcnt lgkmcnt(2)
	v_mfma_f32_32x32x16_bf16 v[48:63], v[162:165], v[100:103], v[48:63]
	s_waitcnt lgkmcnt(1)
	v_mfma_f32_32x32x16_bf16 v[64:79], v[146:149], v[104:107], v[64:79]
	ds_read_b128 v[146:149], v157 offset:20032
	ds_read_b128 v[162:165], v157 offset:20064
	s_waitcnt lgkmcnt(1)
	v_mfma_f32_32x32x16_bf16 v[48:63], v[146:149], v[104:107], v[48:63]
	v_mfma_f32_32x32x16_bf16 v[64:79], v[150:153], v[108:111], v[64:79]
	ds_read_b128 v[146:149], v157 offset:13440
	ds_read_b128 v[150:153], v157 offset:13472
	s_waitcnt lgkmcnt(2)
	v_mfma_f32_32x32x16_bf16 v[48:63], v[162:165], v[108:111], v[48:63]
	s_waitcnt lgkmcnt(1)
	v_mfma_f32_32x32x16_bf16 v[64:79], v[146:149], v[112:115], v[64:79]
	ds_read_b128 v[146:149], v157 offset:20096
	ds_read_b128 v[162:165], v157 offset:20128
	ds_read_b64_tr_b16 v[168:169], v199 offset:0
	ds_read_b64_tr_b16 v[170:171], v199 offset:0x100
	s_waitcnt lgkmcnt(1)
	v_mfma_f32_32x32x16_bf16 v[48:63], v[146:149], v[112:115], v[48:63]
	ds_read_b64_tr_b16 v[146:147], v199 offset:0x800
	ds_read_b64_tr_b16 v[148:149], v199 offset:0x900
	ds_read_b64_tr_b16 v[182:183], v199 offset:0x1000
	ds_read_b64_tr_b16 v[184:185], v199 offset:0x1100
	ds_read_b64_tr_b16 v[186:187], v199 offset:0x1800
	ds_read_b64_tr_b16 v[188:189], v199 offset:0x1900
	ds_read_b64_tr_b16 v[190:191], v199 offset:0x200
	ds_read_b64_tr_b16 v[192:193], v199 offset:0x300
	v_mfma_f32_32x32x16_bf16 v[64:79], v[150:153], v[116:119], v[64:79]
	ds_read_b64_tr_b16 v[150:151], v199 offset:0xa00
	ds_read_b64_tr_b16 v[152:153], v199 offset:0xb00
	ds_read_b64_tr_b16 v[208:209], v199 offset:0x1200
	ds_read_b64_tr_b16 v[210:211], v199 offset:0x1300
	ds_read_b64_tr_b16 v[212:213], v199 offset:0x1a00
	ds_read_b64_tr_b16 v[214:215], v199 offset:0x1b00
	s_waitcnt lgkmcnt(8)
	s_waitcnt lgkmcnt(0)
	v_mfma_f32_32x32x16_bf16 v[48:63], v[162:165], v[116:119], v[48:63]
	v_mfma_f32_32x32x16_bf16 v[0:15], v[92:95], v[168:171], v[0:15]
	s_waitcnt lgkmcnt(0)
	v_mfma_f32_32x32x16_bf16 v[0:15], v[88:91], v[146:149], v[0:15]
	v_mfma_f32_32x32x16_bf16 v[0:15], v[84:87], v[182:185], v[0:15]
	s_waitcnt lgkmcnt(0)
	s_cmp_lg_u32 s40, 0
	s_cbranch_scc0 .Lmla_nobar6
	s_barrier
.Lmla_nobar6:
	v_mfma_f32_32x32x16_bf16 v[0:15], v[80:83], v[186:189], v[0:15]
	v_mfma_f32_32x32x16_bf16 v[16:31], v[92:95], v[190:193], v[16:31]
	s_waitcnt lgkmcnt(0)
	v_mfma_f32_32x32x16_bf16 v[16:31], v[88:91], v[150:153], v[16:31]
	v_mfma_f32_32x32x16_bf16 v[16:31], v[84:87], v[208:211], v[16:31]
	v_mfma_f32_32x32x16_bf16 v[16:31], v[80:83], v[212:215], v[16:31]
	s_cmp_lt_i32 s47, s54
	s_cbranch_scc0 .Lmla_w2_tail
	s_waitcnt vmcnt(3)
	ds_write_b128 v200, v[136:139]
	ds_write_b128 v201, v[132:135] offset:26624
	s_cmp_lg_u32 s8, 0
	s_cbranch_scc0 .LBB0_991
	ds_write_b128 v239, v[140:143] offset:128
.LBB0_991:
	v_exp_f32_e32 v218, v64
	v_exp_f32_e32 v219, v65
	v_exp_f32_e32 v220, v66
	v_exp_f32_e32 v221, v67
	v_add_f32_e32 v173, v218, v220
	v_exp_f32_e32 v222, v68
	v_add_f32_e32 v174, v219, v221
	v_exp_f32_e32 v223, v69
	v_add_f32_e32 v173, v222, v173
	v_exp_f32_e32 v224, v70
	v_add_f32_e32 v174, v223, v174
	v_exp_f32_e32 v225, v71
	v_add_f32_e32 v173, v224, v173
	v_exp_f32_e32 v226, v72
	v_add_f32_e32 v174, v225, v174
	v_exp_f32_e32 v227, v73
	v_add_f32_e32 v173, v226, v173
	v_exp_f32_e32 v228, v74
	v_add_f32_e32 v174, v227, v174
	v_exp_f32_e32 v229, v75
	v_add_f32_e32 v173, v228, v173
	v_exp_f32_e32 v230, v76
	v_add_f32_e32 v174, v229, v174
	v_exp_f32_e32 v231, v77
	v_add_f32_e32 v173, v230, v173
	v_exp_f32_e32 v232, v78
	v_add_f32_e32 v174, v231, v174
	v_exp_f32_e32 v233, v79
	v_add_f32_e32 v173, v232, v173
	v_exp_f32_e32 v234, v48
	v_add_f32_e32 v174, v233, v174
	v_exp_f32_e32 v240, v49
	v_add_f32_e32 v173, v234, v173
	v_exp_f32_e32 v241, v50
	v_add_f32_e32 v174, v240, v174
	v_exp_f32_e32 v242, v51
	v_add_f32_e32 v173, v241, v173
	v_exp_f32_e32 v243, v52
	v_add_f32_e32 v174, v242, v174
	v_exp_f32_e32 v244, v53
	v_add_f32_e32 v173, v243, v173
	v_exp_f32_e32 v245, v54
	v_add_f32_e32 v174, v244, v174
	v_exp_f32_e32 v246, v55
	v_add_f32_e32 v173, v245, v173
	v_exp_f32_e32 v247, v56
	v_add_f32_e32 v174, v246, v174
	v_exp_f32_e32 v248, v57
	v_add_f32_e32 v173, v247, v173
	v_exp_f32_e32 v249, v58
	v_add_f32_e32 v174, v248, v174
	v_exp_f32_e32 v250, v59
	v_add_f32_e32 v173, v249, v173
	v_exp_f32_e32 v251, v60
	v_add_f32_e32 v174, v250, v174
	v_exp_f32_e32 v252, v61
	v_add_f32_e32 v173, v251, v173
	v_exp_f32_e32 v253, v62
	v_add_f32_e32 v174, v252, v174
	v_exp_f32_e32 v172, v63
	v_add_f32_e32 v173, v253, v173
	v_add_f32_e32 v174, v172, v174
	v_add_f32_e32 v173, v173, v174
	v_cmp_ge_f32_e32 vcc, 0x47800000, v173
	s_cmp_eq_u64 vcc, exec
	s_cbranch_scc0 .LBB0_996
	v_add_f32_e32 v236, v236, v173
.Lmla_s2o_done:
	v_cmp_gt_f32_e32 vcc, 1.0, v235
	s_cbranch_vccz .LBB0_964
	s_and_saveexec_b64 s[12:13], s[10:11]
	s_cbranch_execz .LBB0_963
	ds_write_b32 v202, v235 offset:43136
	s_branch .LBB0_963

; __device__ __forceinline__ void mla_softmax_rel_kp(f32x16& p0, f32x16& p1, f32x16& negm, bool first, float& l_reg, float& alpha, bf16x8& pa0, bf16x8& pa1, bf16x8& pa2, bf16x8& pa3) {
;     ...
;     if (__builtin_expect(first || !__all(pmax <= THR2), 0)) {
;         const float d = first ? pmax : fmaxf(pmax, 0.f);
;         if (!first) alpha = __builtin_amdgcn_exp2f(-d);
;         const float nm = negm[0] - d;
; #pragma unroll
;         for (int r = 0; r < 16; ++r) { negm[r] = nm; p0[r] -= d; p1[r] -= d; }
;     }
; #pragma unroll
;     for (int r = 0; r < 16; ++r) { p0[r] = __builtin_amdgcn_exp2f(p0[r]); p1[r] = __builtin_amdgcn_exp2f(p1[r]); }
;     float ps = 0.f;
; #pragma unroll
;     for (int r = 0; r < 16; ++r) ps += p0[r];
; #pragma unroll
;     for (int r = 0; r < 16; ++r) ps += p1[r];
;     { auto rr = __builtin_amdgcn_permlane32_swap(__float_as_uint(ps), __float_as_uint(ps), false, false); ps = __uint_as_float(rr[0]) + __uint_as_float(rr[1]); }
;     l_reg = l_reg * alpha + ps;
.LBB0_995:
	v_max3_f32 v48, v64, v65, v66
	v_max3_f32 v49, v67, v68, v69
	v_max3_f32 v50, v70, v71, v72
	v_max3_f32 v48, v48, v73, v74
	v_max3_f32 v49, v49, v75, v76
	v_max3_f32 v50, v50, v77, v78
	v_max3_f32 v48, v48, v79, v80
	v_max3_f32 v49, v49, v81, v82
	v_max3_f32 v50, v50, v83, v84
	v_max3_f32 v48, v48, v85, v86
	v_max3_f32 v49, v49, v87, v88
	v_max3_f32 v50, v50, v89, v90
	v_max3_f32 v48, v48, v91, v92
	v_max3_f32 v49, v49, v93, v94
	v_max3_f32 v48, v48, v49, v50
	v_max_f32_e32 v48, v48, v95
	v_mov_b32_e32 v49, v48
	s_nop 1
	v_permlane32_swap_b32_e32 v48, v49
	v_max_f32_e32 v48, v48, v49
	v_max_f32_e32 v33, v48, v48
	v_max_f32_e32 v34, 0, v33
	v_exp_f32_e64 v144, -v34
	v_sub_f32_e32 v48, v32, v34
	v_mul_f32_e32 v236, v236, v144
	v_mul_f32_e32 v237, v237, v144
	v_pk_add_f32 v[64:65], v[64:65], v[34:35] op_sel_hi:[1,0] neg_lo:[0,1] neg_hi:[0,1]
	v_pk_add_f32 v[80:81], v[80:81], v[34:35] op_sel_hi:[1,0] neg_lo:[0,1] neg_hi:[0,1]
	v_pk_add_f32 v[66:67], v[66:67], v[34:35] op_sel_hi:[1,0] neg_lo:[0,1] neg_hi:[0,1]
	v_pk_add_f32 v[82:83], v[82:83], v[34:35] op_sel_hi:[1,0] neg_lo:[0,1] neg_hi:[0,1]
	v_pk_add_f32 v[68:69], v[68:69], v[34:35] op_sel_hi:[1,0] neg_lo:[0,1] neg_hi:[0,1]
	v_pk_add_f32 v[84:85], v[84:85], v[34:35] op_sel_hi:[1,0] neg_lo:[0,1] neg_hi:[0,1]
	v_pk_add_f32 v[70:71], v[70:71], v[34:35] op_sel_hi:[1,0] neg_lo:[0,1] neg_hi:[0,1]
	v_pk_add_f32 v[86:87], v[86:87], v[34:35] op_sel_hi:[1,0] neg_lo:[0,1] neg_hi:[0,1]
	v_pk_add_f32 v[72:73], v[72:73], v[34:35] op_sel_hi:[1,0] neg_lo:[0,1] neg_hi:[0,1]
	v_pk_add_f32 v[88:89], v[88:89], v[34:35] op_sel_hi:[1,0] neg_lo:[0,1] neg_hi:[0,1]
	v_pk_add_f32 v[74:75], v[74:75], v[34:35] op_sel_hi:[1,0] neg_lo:[0,1] neg_hi:[0,1]
	v_pk_add_f32 v[90:91], v[90:91], v[34:35] op_sel_hi:[1,0] neg_lo:[0,1] neg_hi:[0,1]
	v_pk_add_f32 v[76:77], v[76:77], v[34:35] op_sel_hi:[1,0] neg_lo:[0,1] neg_hi:[0,1]
	v_pk_add_f32 v[92:93], v[92:93], v[34:35] op_sel_hi:[1,0] neg_lo:[0,1] neg_hi:[0,1]
	v_pk_add_f32 v[78:79], v[78:79], v[34:35] op_sel_hi:[1,0] neg_lo:[0,1] neg_hi:[0,1]
	v_pk_add_f32 v[94:95], v[94:95], v[34:35] op_sel_hi:[1,0] neg_lo:[0,1] neg_hi:[0,1]
	v_mov_b32_e32 v49, v48
	v_mov_b32_e32 v50, v48
	v_mov_b32_e32 v51, v48
	v_mov_b32_e32 v52, v48
	v_mov_b32_e32 v53, v48
	v_mov_b32_e32 v54, v48
	v_mov_b32_e32 v55, v48
	v_mov_b32_e32 v56, v48
	v_mov_b32_e32 v57, v48
	v_mov_b32_e32 v58, v48
	v_mov_b32_e32 v59, v48
	v_mov_b32_e32 v60, v48
	v_mov_b32_e32 v61, v48
	v_mov_b32_e32 v62, v48
	v_mov_b32_e32 v63, v48
	v_mov_b32_e32 v32, v48
	v_mov_b32_e32 v33, v48
	v_mov_b32_e32 v34, v48
	v_mov_b32_e32 v35, v48
	v_mov_b32_e32 v36, v48
	v_mov_b32_e32 v37, v48
	v_mov_b32_e32 v38, v48
	v_mov_b32_e32 v39, v48
	v_mov_b32_e32 v40, v48
	v_mov_b32_e32 v41, v48
	v_mov_b32_e32 v42, v48
	v_mov_b32_e32 v43, v48
	v_mov_b32_e32 v44, v48
	v_mov_b32_e32 v45, v48
	v_mov_b32_e32 v46, v48
	v_mov_b32_e32 v47, v48
	v_exp_f32_e32 v218, v64
	v_exp_f32_e32 v219, v65
	v_exp_f32_e32 v220, v66
	v_add_f32_e32 v236, v218, v236
	v_exp_f32_e32 v221, v67
	v_add_f32_e32 v236, v219, v236
	v_exp_f32_e32 v222, v68
	v_add_f32_e32 v236, v220, v236
	v_exp_f32_e32 v223, v69
	v_add_f32_e32 v236, v221, v236
	v_exp_f32_e32 v224, v70
	v_add_f32_e32 v236, v222, v236
	v_exp_f32_e32 v225, v71
	v_add_f32_e32 v236, v223, v236
	v_exp_f32_e32 v226, v72
	v_add_f32_e32 v236, v224, v236
	v_exp_f32_e32 v227, v73
	v_add_f32_e32 v236, v225, v236
	v_exp_f32_e32 v228, v74
	v_add_f32_e32 v236, v226, v236
	v_exp_f32_e32 v229, v75
	v_add_f32_e32 v236, v227, v236
	v_exp_f32_e32 v230, v76
	v_add_f32_e32 v236, v228, v236
	v_exp_f32_e32 v231, v77
	v_add_f32_e32 v236, v229, v236
	v_exp_f32_e32 v232, v78
	v_add_f32_e32 v236, v230, v236
	v_exp_f32_e32 v233, v79
	v_add_f32_e32 v236, v231, v236
	v_exp_f32_e32 v234, v80
	v_add_f32_e32 v236, v232, v236
	v_exp_f32_e32 v240, v81
	v_add_f32_e32 v236, v233, v236
	v_exp_f32_e32 v241, v82
	v_add_f32_e32 v236, v234, v236
	v_exp_f32_e32 v242, v83
	v_add_f32_e32 v236, v240, v236
	v_exp_f32_e32 v243, v84
	v_add_f32_e32 v236, v241, v236
	v_exp_f32_e32 v244, v85
	v_add_f32_e32 v236, v242, v236
	v_exp_f32_e32 v245, v86
	v_add_f32_e32 v236, v243, v236
	v_exp_f32_e32 v246, v87
	v_add_f32_e32 v236, v244, v236
	v_exp_f32_e32 v247, v88
	v_add_f32_e32 v236, v245, v236
	v_exp_f32_e32 v248, v89
	v_add_f32_e32 v236, v246, v236
	v_exp_f32_e32 v249, v90
	v_add_f32_e32 v236, v247, v236
	v_exp_f32_e32 v250, v91
	v_add_f32_e32 v236, v248, v236
	v_exp_f32_e32 v251, v92
	v_add_f32_e32 v236, v249, v236
	v_exp_f32_e32 v252, v93
	v_add_f32_e32 v236, v250, v236
	v_exp_f32_e32 v253, v94
	v_add_f32_e32 v236, v251, v236
	v_exp_f32_e32 v172, v95
	v_add_f32_e32 v236, v252, v236
	v_add_f32_e32 v236, v253, v236
	v_add_f32_e32 v236, v172, v236
	s_branch .Lmla_s2e_done
; __device__ __forceinline__ unsigned cvt_pk_bf16(float lo, float hi) { unsigned r; asm volatile("v_cvt_pk_bf16_f32 %0, %1, %2" : "=v"(r) : "v"(lo), "v"(hi)); return r; }
; __device__ __forceinline__ bf16x8 pack8(const f32x16& p, int base) {
;     u32x4 w = {cvt_pk_bf16(p[base + 0], p[base + 1]), cvt_pk_bf16(p[base + 2], p[base + 3]), cvt_pk_bf16(p[base + 4], p[base + 5]), cvt_pk_bf16(p[base + 6], p[base + 7])};
;     return *reinterpret_cast<bf16x8*>(&w);
; }
; __device__ __forceinline__ void mla_softmax_rel_kp(f32x16& p0, f32x16& p1, f32x16& negm, bool first, float& l_reg, float& alpha, bf16x8& pa0, bf16x8& pa1, bf16x8& pa2, bf16x8& pa3) {
;     ...
;     if (__builtin_expect(first || !__all(pmax <= THR2), 0)) {
;         const float d = first ? pmax : fmaxf(pmax, 0.f);
;         if (!first) alpha = __builtin_amdgcn_exp2f(-d);
;         const float nm = negm[0] - d;
; #pragma unroll
;         for (int r = 0; r < 16; ++r) { negm[r] = nm; p0[r] -= d; p1[r] -= d; }
;     }
; #pragma unroll
;     for (int r = 0; r < 16; ++r) { p0[r] = __builtin_amdgcn_exp2f(p0[r]); p1[r] = __builtin_amdgcn_exp2f(p1[r]); }
;     float ps = 0.f;
; #pragma unroll
;     for (int r = 0; r < 16; ++r) ps += p0[r];
; #pragma unroll
;     for (int r = 0; r < 16; ++r) ps += p1[r];
;     { auto rr = __builtin_amdgcn_permlane32_swap(__float_as_uint(ps), __float_as_uint(ps), false, false); ps = __uint_as_float(rr[0]) + __uint_as_float(rr[1]); }
;     l_reg = l_reg * alpha + ps;
;     pa0 = pack8(p0, 0); pa1 = pack8(p0, 8); pa2 = pack8(p1, 0); pa3 = pack8(p1, 8);
.LBB0_996:
	v_max3_f32 v81, v64, v65, v66
	v_max3_f32 v82, v67, v68, v69
	v_max3_f32 v83, v70, v71, v72
	v_max3_f32 v81, v81, v73, v74
	v_max3_f32 v82, v82, v75, v76
	v_max3_f32 v83, v83, v77, v78
	v_max3_f32 v81, v81, v79, v48
	v_max3_f32 v82, v82, v49, v50
	v_max3_f32 v83, v83, v51, v52
	v_max3_f32 v81, v81, v53, v54
	v_max3_f32 v82, v82, v55, v56
	v_max3_f32 v83, v83, v57, v58
	v_max3_f32 v81, v81, v59, v60
	v_max3_f32 v82, v82, v61, v62
	v_max3_f32 v81, v81, v82, v83
	v_max_f32_e32 v81, v81, v63
	v_mov_b32_e32 v82, v81
	s_nop 1
	v_permlane32_swap_b32_e32 v81, v82
	v_max_f32_e32 v81, v81, v82
	v_max_f32_e32 v33, v81, v81
	v_max_f32_e32 v34, 0, v33
	v_exp_f32_e64 v235, -v34
	v_sub_f32_e32 v32, v32, v34
	v_mul_f32_e32 v236, v236, v235
	v_mul_f32_e32 v237, v237, v235
	v_pk_add_f32 v[64:65], v[64:65], v[34:35] op_sel_hi:[1,0] neg_lo:[0,1] neg_hi:[0,1]
	v_pk_add_f32 v[48:49], v[48:49], v[34:35] op_sel_hi:[1,0] neg_lo:[0,1] neg_hi:[0,1]
	v_pk_add_f32 v[66:67], v[66:67], v[34:35] op_sel_hi:[1,0] neg_lo:[0,1] neg_hi:[0,1]
	v_pk_add_f32 v[50:51], v[50:51], v[34:35] op_sel_hi:[1,0] neg_lo:[0,1] neg_hi:[0,1]
	v_pk_add_f32 v[68:69], v[68:69], v[34:35] op_sel_hi:[1,0] neg_lo:[0,1] neg_hi:[0,1]
	v_pk_add_f32 v[52:53], v[52:53], v[34:35] op_sel_hi:[1,0] neg_lo:[0,1] neg_hi:[0,1]
	v_pk_add_f32 v[70:71], v[70:71], v[34:35] op_sel_hi:[1,0] neg_lo:[0,1] neg_hi:[0,1]
	v_pk_add_f32 v[54:55], v[54:55], v[34:35] op_sel_hi:[1,0] neg_lo:[0,1] neg_hi:[0,1]
	v_pk_add_f32 v[72:73], v[72:73], v[34:35] op_sel_hi:[1,0] neg_lo:[0,1] neg_hi:[0,1]
	v_pk_add_f32 v[56:57], v[56:57], v[34:35] op_sel_hi:[1,0] neg_lo:[0,1] neg_hi:[0,1]
	v_pk_add_f32 v[74:75], v[74:75], v[34:35] op_sel_hi:[1,0] neg_lo:[0,1] neg_hi:[0,1]
	v_pk_add_f32 v[58:59], v[58:59], v[34:35] op_sel_hi:[1,0] neg_lo:[0,1] neg_hi:[0,1]
	v_pk_add_f32 v[76:77], v[76:77], v[34:35] op_sel_hi:[1,0] neg_lo:[0,1] neg_hi:[0,1]
	v_pk_add_f32 v[60:61], v[60:61], v[34:35] op_sel_hi:[1,0] neg_lo:[0,1] neg_hi:[0,1]
	v_pk_add_f32 v[78:79], v[78:79], v[34:35] op_sel_hi:[1,0] neg_lo:[0,1] neg_hi:[0,1]
	v_pk_add_f32 v[62:63], v[62:63], v[34:35] op_sel_hi:[1,0] neg_lo:[0,1] neg_hi:[0,1]
	v_mov_b32_e32 v33, v32
	v_mov_b32_e32 v34, v32
	v_mov_b32_e32 v35, v32
	v_mov_b32_e32 v36, v32
	v_mov_b32_e32 v37, v32
	v_mov_b32_e32 v38, v32
	v_mov_b32_e32 v39, v32
	v_mov_b32_e32 v40, v32
	v_mov_b32_e32 v41, v32
	v_mov_b32_e32 v42, v32
	v_mov_b32_e32 v43, v32
	v_mov_b32_e32 v44, v32
	v_mov_b32_e32 v45, v32
	v_mov_b32_e32 v46, v32
	v_mov_b32_e32 v47, v32
	v_exp_f32_e32 v218, v64
	v_exp_f32_e32 v219, v65
	v_exp_f32_e32 v220, v66
	v_add_f32_e32 v236, v218, v236
	v_exp_f32_e32 v221, v67
	v_add_f32_e32 v236, v219, v236
	v_exp_f32_e32 v222, v68
	v_add_f32_e32 v236, v220, v236
	v_exp_f32_e32 v223, v69
	v_add_f32_e32 v236, v221, v236
	v_exp_f32_e32 v224, v70
	v_add_f32_e32 v236, v222, v236
	v_exp_f32_e32 v225, v71
	v_add_f32_e32 v236, v223, v236
	v_exp_f32_e32 v226, v72
	v_add_f32_e32 v236, v224, v236
	v_exp_f32_e32 v227, v73
	v_add_f32_e32 v236, v225, v236
	v_exp_f32_e32 v228, v74
	v_add_f32_e32 v236, v226, v236
	v_exp_f32_e32 v229, v75
	v_add_f32_e32 v236, v227, v236
	v_exp_f32_e32 v230, v76
	v_add_f32_e32 v236, v228, v236
	v_exp_f32_e32 v231, v77
	v_add_f32_e32 v236, v229, v236
	v_exp_f32_e32 v232, v78
	v_add_f32_e32 v236, v230, v236
	v_exp_f32_e32 v233, v79
	v_add_f32_e32 v236, v231, v236
	v_exp_f32_e32 v234, v48
	v_add_f32_e32 v236, v232, v236
	v_exp_f32_e32 v240, v49
	v_add_f32_e32 v236, v233, v236
	v_exp_f32_e32 v241, v50
	v_add_f32_e32 v236, v234, v236
	v_exp_f32_e32 v242, v51
	v_add_f32_e32 v236, v240, v236
	v_exp_f32_e32 v243, v52
	v_add_f32_e32 v236, v241, v236
	v_exp_f32_e32 v244, v53
	v_add_f32_e32 v236, v242, v236
	v_exp_f32_e32 v245, v54
	v_add_f32_e32 v236, v243, v236
	v_exp_f32_e32 v246, v55
	v_add_f32_e32 v236, v244, v236
	v_exp_f32_e32 v247, v56
	v_add_f32_e32 v236, v245, v236
	v_exp_f32_e32 v248, v57
	v_add_f32_e32 v236, v246, v236
	v_exp_f32_e32 v249, v58
	v_add_f32_e32 v236, v247, v236
	v_exp_f32_e32 v250, v59
	v_add_f32_e32 v236, v248, v236
	v_exp_f32_e32 v251, v60
	v_add_f32_e32 v236, v249, v236
	v_exp_f32_e32 v252, v61
	v_add_f32_e32 v236, v250, v236
	v_exp_f32_e32 v253, v62
	v_add_f32_e32 v236, v251, v236
	v_exp_f32_e32 v172, v63
	v_add_f32_e32 v236, v252, v236
	v_add_f32_e32 v236, v253, v236
	v_add_f32_e32 v236, v172, v236
	s_branch .Lmla_s2o_done
.Lmla_exit_pack:
	v_cvt_pk_bf16_f32 v55, v245, v246
	v_cvt_pk_bf16_f32 v54, v243, v244
	v_cvt_pk_bf16_f32 v52, v234, v240
	v_cvt_pk_bf16_f32 v53, v241, v242
	v_cvt_pk_bf16_f32 v48, v247, v248
	v_cvt_pk_bf16_f32 v49, v249, v250
	v_cvt_pk_bf16_f32 v50, v251, v252
	v_cvt_pk_bf16_f32 v51, v253, v172
	v_cvt_pk_bf16_f32 v60, v218, v219
	v_cvt_pk_bf16_f32 v61, v220, v221
	v_cvt_pk_bf16_f32 v62, v222, v223
	v_cvt_pk_bf16_f32 v63, v224, v225
	v_cvt_pk_bf16_f32 v56, v226, v227
	v_cvt_pk_bf16_f32 v57, v228, v229
	v_cvt_pk_bf16_f32 v58, v230, v231
	v_cvt_pk_bf16_f32 v59, v232, v233
